# rmsnorm+adaLN row loops rewritten by hand: scalar row addressing, next row prefetched, all modulation-table loads issued up front (layers 1-3 norm0, all norm1)
# speedup vs baseline: 1.0781x; 1.0363x over previous
.LBB0_159:
	v_mov_b32_e32 v0, v188
	v_readlane_b32 s0, v253, 49
	v_ashrrev_i32_e32 v2, 6, v0
	s_mul_i32 s25, s58, 9
	v_add_u32_e32 v18, s0, v2
	s_movk_i32 s0, 0x4800
	v_cmp_gt_i32_e32 vcc, s0, v18
	s_and_saveexec_b64 s[34:35], vcc
	v_writelane_b32 v253, s58, 19
	s_cbranch_execz .LBB0_172
	s_cmp_eq_u32 s58, 0
	s_cselect_b64 s[36:37], -1, 0
	s_cmp_lg_u32 s58, 0
	v_readlane_b32 s0, v253, 19
	v_cmp_lt_i32_e32 vcc, v193, v192
	s_cselect_b64 s[38:39], -1, 0
	s_lshl_b32 s60, s0, 10
	v_readlane_b32 s40, v252, 18
	v_cndmask_b32_e32 v3, v191, v193, vcc
	v_cmp_lt_i32_e32 vcc, v194, v192
	s_lshl_b64 s[0:1], s[60:61], 2
	v_readlane_b32 s52, v252, 30
	v_lshlrev_b32_e32 v34, 2, v3
	v_cndmask_b32_e32 v3, v191, v194, vcc
	v_cmp_lt_i32_e32 vcc, v195, v192
	v_readlane_b32 s53, v252, 31
	s_add_u32 s0, s52, s0
	v_and_b32_e32 v2, 63, v0
	v_lshlrev_b32_e32 v35, 2, v3
	v_cndmask_b32_e32 v3, v191, v195, vcc
	v_cmp_lt_i32_e32 vcc, v196, v192
	s_addc_u32 s1, s53, s1
	v_lshlrev_b32_e32 v0, 4, v2
	v_lshlrev_b32_e32 v36, 2, v3
	v_cndmask_b32_e32 v3, v191, v196, vcc
	v_cmp_lt_i32_e32 vcc, v197, v192
	v_readlane_b32 s48, v252, 26
	v_readlane_b32 s49, v252, 27
	v_readlane_b32 s50, v252, 28
	v_readlane_b32 s51, v252, 29
	v_lshlrev_b32_e32 v4, 2, v2
	v_lshl_add_u64 v[20:21], s[0:1], 0, v[0:1]
	v_lshlrev_b32_e32 v37, 2, v3
	v_cndmask_b32_e32 v3, v191, v197, vcc
	v_cmp_lt_i32_e32 vcc, v198, v192
	v_readlane_b32 s0, v253, 40
	v_readlane_b32 s41, v252, 19
	v_readlane_b32 s48, v252, 14
	v_readlane_b32 s50, v251, 2
	v_readlane_b32 s22, v253, 47
	v_lshlrev_b32_e32 v38, 2, v3
	v_cndmask_b32_e32 v3, v191, v198, vcc
	v_or_b32_e32 v6, 0x100, v4
	v_or_b32_e32 v8, 0x200, v4
	v_or_b32_e32 v10, 0x300, v4
	v_lshl_add_u64 v[22:23], s[94:95], 0, v[0:1]
	v_lshlrev_b32_e32 v0, 3, v2
	v_readlane_b32 s1, v253, 41
	v_readlane_b32 s58, v253, 19
	s_mov_b32 s19, 0x800000
	v_readlane_b32 s49, v252, 15
	v_readlane_b32 s51, v251, 3
	v_readlane_b32 s23, v253, 48
	v_lshlrev_b32_e32 v39, 2, v3
	v_lshl_add_u64 v[24:25], s[0:1], 0, v[0:1]
	s_mov_b64 s[40:41], 0
	v_lshlrev_b32_e32 v0, 4, v2
	v_lshlrev_b32_e32 v26, 2, v4
	v_lshlrev_b32_e32 v28, 2, v6
	v_lshlrev_b32_e32 v30, 2, v8
	v_lshlrev_b32_e32 v32, 2, v10
	v_readlane_b32 s42, v252, 20
	v_readlane_b32 s43, v252, 21
	v_readlane_b32 s44, v252, 22
	v_readlane_b32 s45, v252, 23
	v_readlane_b32 s46, v252, 24
	v_readlane_b32 s47, v252, 25
	v_readlane_b32 s54, v252, 32
	v_readlane_b32 s55, v252, 33
	s_cmp_lg_u32 s58, 0
	s_cbranch_scc0 .LBB0_164
	v_and_b32_e32 v96, 63, v188
	v_lshlrev_b32_e32 v2, 4, v96
	v_lshlrev_b32_e32 v3, 3, v96
	v_lshlrev_b32_e32 v100, 2, v96
	v_xor_b32_e32 v4, 0x80, v100
	v_xor_b32_e32 v5, 0x40, v100
	v_xor_b32_e32 v6, 0x20, v100
	v_xor_b32_e32 v7, 0x10, v100
	v_xor_b32_e32 v8, 0x8, v100
	v_xor_b32_e32 v9, 0x4, v100
	v_readfirstlane_b32 s98, v18
	v_mov_b32_e32 v110, v24
	v_mov_b32_e32 v111, v25
	s_movk_i32 s99, 0x4800
	s_mul_i32 s0, s25, 0x6000
	s_add_u32 s100, s22, s0
	s_addc_u32 s101, s23, 0
	v_readfirstlane_b32 s0, v20
	v_readfirstlane_b32 s1, v21
	s_nop 4
	global_load_dwordx4 v[48:51], v2, s[0:1]
	global_load_dwordx4 v[52:55], v2, s[0:1] offset:1024
	global_load_dwordx4 v[56:59], v2, s[0:1] offset:2048
	global_load_dwordx4 v[60:63], v2, s[0:1] offset:3072
	s_lshl_b32 s2, s98, 12
	s_add_u32 s2, s94, s2
	s_addc_u32 s3, s95, 0
	global_load_dwordx4 v[32:35], v2, s[2:3]
	global_load_dwordx4 v[36:39], v2, s[2:3] offset:1024
	global_load_dwordx4 v[40:43], v2, s[2:3] offset:2048
	global_load_dwordx4 v[44:47], v2, s[2:3] offset:3072
	s_waitcnt vmcnt(0)
	s_branch .Lnbody_0
.Lntop_0:
	s_waitcnt vmcnt(4)
.Lnbody_0:
	v_mov_b32_e32 v16, v32
	v_mov_b32_e32 v17, v33
	v_mov_b32_e32 v18, v34
	v_mov_b32_e32 v19, v35
	v_mov_b32_e32 v20, v36
	v_mov_b32_e32 v21, v37
	v_mov_b32_e32 v22, v38
	v_mov_b32_e32 v23, v39
	v_mov_b32_e32 v24, v40
	v_mov_b32_e32 v25, v41
	v_mov_b32_e32 v26, v42
	v_mov_b32_e32 v27, v43
	v_mov_b32_e32 v28, v44
	v_mov_b32_e32 v29, v45
	v_mov_b32_e32 v30, v46
	v_mov_b32_e32 v31, v47
	s_min_u32 s0, s98, 0x4000
	s_lshr_b32 s0, s0, 11
	s_mul_i32 s0, s0, 0x6000
	s_add_u32 s2, s100, s0
	s_addc_u32 s3, s101, 0
	global_load_dwordx4 v[80:83], v2, s[2:3]
	global_load_dwordx4 v[84:87], v2, s[2:3] offset:1024
	global_load_dwordx4 v[88:91], v2, s[2:3] offset:2048
	global_load_dwordx4 v[92:95], v2, s[2:3] offset:3072
	s_add_u32 s0, s2, 0x1000
	s_addc_u32 s1, s3, 0
	global_load_dwordx4 v[64:67], v2, s[0:1]
	global_load_dwordx4 v[68:71], v2, s[0:1] offset:1024
	global_load_dwordx4 v[72:75], v2, s[0:1] offset:2048
	global_load_dwordx4 v[76:79], v2, s[0:1] offset:3072
	s_add_u32 s2, s98, s91
	s_cmp_lt_u32 s2, s99
	s_cselect_b32 s0, s2, s98
	s_lshl_b32 s0, s0, 12
	s_add_u32 s0, s94, s0
	s_addc_u32 s1, s95, 0
	global_load_dwordx4 v[32:35], v2, s[0:1]
	global_load_dwordx4 v[36:39], v2, s[0:1] offset:1024
	global_load_dwordx4 v[40:43], v2, s[0:1] offset:2048
	global_load_dwordx4 v[44:47], v2, s[0:1] offset:3072
	v_mul_f32_e32 v97, v16, v16
	v_mul_f32_e32 v98, v20, v20
	v_mul_f32_e32 v99, v24, v24
	v_mul_f32_e32 v100, v28, v28
	v_fmac_f32_e32 v97, v17, v17
	v_fmac_f32_e32 v98, v21, v21
	v_fmac_f32_e32 v99, v25, v25
	v_fmac_f32_e32 v100, v29, v29
	v_fmac_f32_e32 v97, v18, v18
	v_fmac_f32_e32 v98, v22, v22
	v_fmac_f32_e32 v99, v26, v26
	v_fmac_f32_e32 v100, v30, v30
	v_fmac_f32_e32 v97, v19, v19
	v_fmac_f32_e32 v98, v23, v23
	v_fmac_f32_e32 v99, v27, v27
	v_fmac_f32_e32 v100, v31, v31
	v_add_f32_e32 v97, v97, v98
	v_add_f32_e32 v99, v99, v100
	v_add_f32_e32 v96, v97, v99
	ds_bpermute_b32 v97, v4, v96
	s_waitcnt lgkmcnt(0)
	v_add_f32_e32 v96, v96, v97
	ds_bpermute_b32 v97, v5, v96
	s_waitcnt lgkmcnt(0)
	v_add_f32_e32 v96, v96, v97
	ds_bpermute_b32 v97, v6, v96
	s_waitcnt lgkmcnt(0)
	v_add_f32_e32 v96, v96, v97
	ds_bpermute_b32 v97, v7, v96
	s_waitcnt lgkmcnt(0)
	v_add_f32_e32 v96, v96, v97
	ds_bpermute_b32 v97, v8, v96
	s_waitcnt lgkmcnt(0)
	v_add_f32_e32 v96, v96, v97
	ds_bpermute_b32 v97, v9, v96
	s_waitcnt lgkmcnt(0)
	v_add_f32_e32 v96, v96, v97
	v_fmamk_f32 v96, v96, 0x3a800000, v189
	v_rsq_f32_e32 v96, v96
	v_readfirstlane_b32 s0, v110
	v_readfirstlane_b32 s1, v111
	s_lshl_b32 s3, s98, 11
	s_add_u32 s0, s0, s3
	s_addc_u32 s1, s1, 0
	s_waitcnt vmcnt(4)
	v_mul_f32_e32 v16, v16, v96
	v_mul_f32_e32 v17, v17, v96
	v_mul_f32_e32 v18, v18, v96
	v_mul_f32_e32 v19, v19, v96
	v_mul_f32_e32 v20, v20, v96
	v_mul_f32_e32 v21, v21, v96
	v_mul_f32_e32 v22, v22, v96
	v_mul_f32_e32 v23, v23, v96
	v_mul_f32_e32 v24, v24, v96
	v_mul_f32_e32 v25, v25, v96
	v_mul_f32_e32 v26, v26, v96
	v_mul_f32_e32 v27, v27, v96
	v_mul_f32_e32 v28, v28, v96
	v_mul_f32_e32 v29, v29, v96
	v_mul_f32_e32 v30, v30, v96
	v_mul_f32_e32 v31, v31, v96
	v_mul_f32_e32 v16, v16, v48
	v_mul_f32_e32 v17, v17, v49
	v_mul_f32_e32 v18, v18, v50
	v_mul_f32_e32 v19, v19, v51
	v_mul_f32_e32 v20, v20, v52
	v_mul_f32_e32 v21, v21, v53
	v_mul_f32_e32 v22, v22, v54
	v_mul_f32_e32 v23, v23, v55
	v_mul_f32_e32 v24, v24, v56
	v_mul_f32_e32 v25, v25, v57
	v_mul_f32_e32 v26, v26, v58
	v_mul_f32_e32 v27, v27, v59
	v_mul_f32_e32 v28, v28, v60
	v_mul_f32_e32 v29, v29, v61
	v_mul_f32_e32 v30, v30, v62
	v_mul_f32_e32 v31, v31, v63
	v_add_f32_e32 v64, 1.0, v64
	v_add_f32_e32 v65, 1.0, v65
	v_add_f32_e32 v66, 1.0, v66
	v_add_f32_e32 v67, 1.0, v67
	v_add_f32_e32 v68, 1.0, v68
	v_add_f32_e32 v69, 1.0, v69
	v_add_f32_e32 v70, 1.0, v70
	v_add_f32_e32 v71, 1.0, v71
	v_add_f32_e32 v72, 1.0, v72
	v_add_f32_e32 v73, 1.0, v73
	v_add_f32_e32 v74, 1.0, v74
	v_add_f32_e32 v75, 1.0, v75
	v_add_f32_e32 v76, 1.0, v76
	v_add_f32_e32 v77, 1.0, v77
	v_add_f32_e32 v78, 1.0, v78
	v_add_f32_e32 v79, 1.0, v79
	v_fma_f32 v16, v16, v64, v80
	v_fma_f32 v17, v17, v65, v81
	v_fma_f32 v18, v18, v66, v82
	v_fma_f32 v19, v19, v67, v83
	v_fma_f32 v20, v20, v68, v84
	v_fma_f32 v21, v21, v69, v85
	v_fma_f32 v22, v22, v70, v86
	v_fma_f32 v23, v23, v71, v87
	v_fma_f32 v24, v24, v72, v88
	v_fma_f32 v25, v25, v73, v89
	v_fma_f32 v26, v26, v74, v90
	v_fma_f32 v27, v27, v75, v91
	v_fma_f32 v28, v28, v76, v92
	v_fma_f32 v29, v29, v77, v93
	v_fma_f32 v30, v30, v78, v94
	v_fma_f32 v31, v31, v79, v95
	v_cvt_pk_bf16_f32 v102, v16, v17
	v_cvt_pk_bf16_f32 v103, v18, v19
	v_cvt_pk_bf16_f32 v104, v20, v21
	v_cvt_pk_bf16_f32 v105, v22, v23
	v_cvt_pk_bf16_f32 v106, v24, v25
	v_cvt_pk_bf16_f32 v107, v26, v27
	v_cvt_pk_bf16_f32 v108, v28, v29
	v_cvt_pk_bf16_f32 v109, v30, v31
	global_store_dwordx2 v3, v[102:103], s[0:1]
	global_store_dwordx2 v3, v[104:105], s[0:1] offset:512
	global_store_dwordx2 v3, v[106:107], s[0:1] offset:1024
	global_store_dwordx2 v3, v[108:109], s[0:1] offset:1536
	s_mov_b32 s98, s2
	s_cmp_lt_u32 s98, s99
	s_cbranch_scc1 .Lntop_0
	s_branch .LBB0_172

.LBB0_220:
	s_or_b64 exec, exec, s[34:35]
	v_readlane_b32 s0, v254, 20
	v_readlane_b32 s1, v254, 21
	v_mov_b32_e32 v2, v188
	s_andn2_b64 vcc, exec, s[0:1]
	s_waitcnt lgkmcnt(0)
	s_barrier
	s_cbranch_vccnz .LBB0_245
	s_mul_i32 s0, s58, 0x280000
	v_readlane_b32 s1, v254, 22
	s_add_u32 s34, s1, s0
	v_readlane_b32 s0, v254, 23
	s_addc_u32 s35, s0, 0
	v_and_b32_e32 v3, 63, v2
	v_ashrrev_i32_e32 v20, 6, v2
	v_readlane_b32 s0, v254, 28
	v_bfe_u32 v21, v2, 3, 3
	v_readlane_b32 s1, v254, 29
	s_add_u32 s0, s34, s0
	v_bitop3_b32 v0, v21, v2, 7 bitop3:0x78
	v_readlane_b32 s2, v254, 26
	v_lshl_add_u32 v95, v3, 4, 0
	v_lshl_or_b32 v8, v20, 5, v21
	s_addc_u32 s1, s35, s1
	v_lshlrev_b32_e32 v0, 4, v0
	v_readlane_b32 s3, v254, 27
	v_ashrrev_i32_e32 v9, 31, v8
	v_lshl_add_u32 v138, v20, 12, v95
	v_lshlrev_b32_e32 v22, 2, v20
	v_lshl_add_u64 v[4:5], s[2:3], 0, v[0:1]
	v_lshl_add_u64 v[6:7], s[0:1], 0, v[0:1]
	v_lshlrev_b64 v[10:11], 11, v[8:9]
	v_readfirstlane_b32 s0, v138
	v_lshl_add_u64 v[12:13], v[4:5], 0, v[10:11]
	v_add_u32_e32 v139, 0x8000, v138
	s_mov_b32 m0, s0
	v_or_b32_e32 v3, 1, v22
	global_load_lds_dwordx4 v[12:13], off
	v_readfirstlane_b32 s0, v139
	v_lshl_or_b32 v12, v3, 3, v21
	v_lshl_add_u64 v[14:15], v[6:7], 0, v[10:11]
	s_mov_b32 m0, s0
	v_ashrrev_i32_e32 v13, 31, v12
	v_lshl_add_u32 v140, v3, 10, v95
	global_load_lds_dwordx4 v[14:15], off
	v_lshlrev_b64 v[14:15], 11, v[12:13]
	v_add_u32_e32 v141, 0x8000, v140
	v_readfirstlane_b32 s0, v140
	v_lshl_add_u64 v[16:17], v[4:5], 0, v[14:15]
	s_mov_b32 m0, s0
	v_readfirstlane_b32 s0, v141
	v_lshl_add_u64 v[14:15], v[6:7], 0, v[14:15]
	global_load_lds_dwordx4 v[16:17], off
	s_mov_b32 m0, s0
	v_or_b32_e32 v23, 2, v22
	global_load_lds_dwordx4 v[14:15], off
	v_lshl_or_b32 v14, v23, 3, v21
	v_ashrrev_i32_e32 v15, 31, v14
	v_lshl_add_u32 v142, v23, 10, v95
	v_lshlrev_b64 v[16:17], 11, v[14:15]
	v_add_u32_e32 v143, 0x8000, v142
	v_readfirstlane_b32 s0, v142
	v_lshl_add_u64 v[18:19], v[4:5], 0, v[16:17]
	s_mov_b32 m0, s0
	v_readfirstlane_b32 s0, v143
	v_lshl_add_u64 v[16:17], v[6:7], 0, v[16:17]
	global_load_lds_dwordx4 v[18:19], off
	s_mov_b32 m0, s0
	v_or_b32_e32 v22, 3, v22
	global_load_lds_dwordx4 v[16:17], off
	v_lshl_or_b32 v16, v22, 3, v21
	v_ashrrev_i32_e32 v17, 31, v16
	v_lshl_add_u32 v144, v22, 10, v95
	v_lshlrev_b64 v[18:19], 11, v[16:17]
	v_add_u32_e32 v145, 0x8000, v144
	v_readfirstlane_b32 s0, v144
	v_lshl_add_u64 v[4:5], v[4:5], 0, v[18:19]
	s_mov_b32 m0, s0
	v_readfirstlane_b32 s0, v145
	v_lshl_add_u64 v[6:7], v[6:7], 0, v[18:19]
	global_load_lds_dwordx4 v[4:5], off
	s_mov_b32 m0, s0
	v_and_b32_e32 v146, 15, v2
	global_load_lds_dwordx4 v[6:7], off
	v_bfe_u32 v18, v2, 4, 2
	v_ashrrev_i32_e32 v21, 7, v2
	v_and_b32_e32 v19, 1, v20
	v_and_b32_e32 v24, 7, v2
	v_lshlrev_b64 v[4:5], 10, v[8:9]
	v_lshlrev_b32_e32 v148, 9, v3
	v_lshlrev_b32_e32 v3, 13, v21
	v_lshlrev_b32_e32 v9, 7, v146
	v_bitop3_b32 v2, v18, v2, 7 bitop3:0x78
	v_add3_u32 v151, 0, v3, v9
	v_lshlrev_b32_e32 v3, 13, v19
	v_lshlrev_b32_e32 v157, 4, v2
	v_bitop3_b32 v2, v18, v24, 4 bitop3:0x36
	v_add3_u32 v152, 0, v3, v9
	v_lshlrev_b32_e32 v158, 4, v2
	v_lshl_or_b32 v2, v18, 5, v9
	v_mov_b32_e32 v3, v1
	v_lshlrev_b64 v[6:7], 10, v[12:13]
	v_lshlrev_b64 v[12:13], 10, v[14:15]
	v_lshlrev_b64 v[14:15], 10, v[16:17]
	v_readlane_b32 s0, v253, 40
	v_lshl_add_u64 v[96:97], s[16:17], 0, v[2:3]
	v_or_b32_e32 v2, 8, v8
	v_or_b32_e32 v16, 16, v8
	v_or_b32_e32 v8, 24, v8
	v_readlane_b32 s1, v253, 41
	v_ashrrev_i32_e32 v3, 31, v2
	v_ashrrev_i32_e32 v17, 31, v16
	v_ashrrev_i32_e32 v9, 31, v8
	v_lshl_add_u64 v[90:91], s[0:1], 0, v[0:1]
	v_readlane_b32 s0, v254, 44
	v_lshlrev_b64 v[2:3], 11, v[2:3]
	v_lshlrev_b64 v[16:17], 11, v[16:17]
	v_lshlrev_b64 v[8:9], 11, v[8:9]
	v_or_b32_e32 v10, v10, v0
	v_readlane_b32 s1, v254, 45
	v_or_b32_e32 v2, v2, v0
	v_or_b32_e32 v16, v16, v0
	v_or_b32_e32 v8, v8, v0
	v_lshl_add_u64 v[98:99], s[0:1], 0, v[10:11]
	v_lshl_add_u64 v[100:101], s[0:1], 0, v[2:3]
	v_lshl_add_u64 v[102:103], s[0:1], 0, v[16:17]
	v_lshl_add_u64 v[104:105], s[0:1], 0, v[8:9]
	v_readlane_b32 s0, v254, 46
	s_lshl_b32 s60, s58, 6
	v_lshlrev_b32_e32 v94, 2, v18
	v_lshlrev_b32_e32 v154, 6, v21
	v_readlane_b32 s1, v254, 47
	v_lshlrev_b32_e32 v147, 11, v20
	v_lshlrev_b32_e32 v149, 9, v23
	v_lshlrev_b32_e32 v150, 9, v22
	v_lshl_add_u64 v[92:93], s[34:35], 0, v[0:1]
	v_lshlrev_b32_e32 v153, 6, v19
	v_or_b32_e32 v155, v154, v146
	v_or_b32_e32 v156, 0xfffffb80, v94
	v_lshl_add_u64 v[106:107], s[0:1], 0, v[10:11]
	v_lshl_add_u64 v[108:109], s[0:1], 0, v[2:3]
	v_lshl_add_u64 v[110:111], s[0:1], 0, v[16:17]
	v_lshl_add_u64 v[112:113], s[0:1], 0, v[8:9]
	v_lshlrev_b64 v[114:115], 1, v[4:5]
	v_lshlrev_b64 v[116:117], 1, v[6:7]
	v_lshlrev_b64 v[118:119], 1, v[12:13]
	v_lshlrev_b64 v[120:121], 1, v[14:15]
	s_lshl_b64 s[34:35], s[60:61], 2
	s_mov_b32 s33, 0x800000
	v_readlane_b32 s0, v253, 4
	s_waitcnt vmcnt(0)
	s_branch .LBB0_223

.LBB0_225:
	s_and_b32 s1, s0, 7
	s_mulk_i32 s1, 0xb4
	s_ashr_i32 s0, s0, 3
	s_add_i32 s1, s1, s0
	s_mul_hi_i32 s0, s1, 0x66666667
	s_lshr_b32 s3, s0, 31
	s_ashr_i32 s0, s0, 5
	s_add_i32 s0, s0, s3
	s_mul_i32 s3, s0, 0x50
	s_sub_i32 s1, s1, s3
	s_lshl_b32 s19, s0, 10
	s_lshl_b32 s0, s1, 7
	s_and_b32 s22, s0, 0x380
	s_lshl_b32 s3, s1, 4
	s_and_b32 s38, s3, 0xffffff80
	s_or_b32 s40, s19, s22
	s_ashr_i32 s39, s38, 31
	s_waitcnt vmcnt(16)
	s_ashr_i32 s41, s40, 31
	s_lshl_b64 s[0:1], s[38:39], 11
	s_lshl_b64 s[22:23], s[40:41], 11
	v_mov_b32_e32 v2, 0
	v_lshl_add_u64 v[66:67], v[98:99], 0, s[22:23]
	v_lshl_add_u64 v[68:69], v[100:101], 0, s[22:23]
	v_lshl_add_u64 v[70:71], v[102:103], 0, s[22:23]
	v_lshl_add_u64 v[72:73], v[104:105], 0, s[22:23]
	v_lshl_add_u64 v[74:75], v[106:107], 0, s[0:1]
	v_lshl_add_u64 v[76:77], v[108:109], 0, s[0:1]
	v_lshl_add_u64 v[78:79], v[110:111], 0, s[0:1]
	v_lshl_add_u64 v[80:81], v[112:113], 0, s[0:1]
	s_mov_b32 s19, 0
	v_mov_b32_e32 v3, v2
	v_mov_b32_e32 v4, v2
	v_mov_b32_e32 v5, v2
	v_mov_b32_e32 v6, v2
	v_mov_b32_e32 v7, v2
	v_mov_b32_e32 v8, v2
	v_mov_b32_e32 v9, v2
	v_mov_b32_e32 v10, v2
	v_mov_b32_e32 v11, v2
	v_mov_b32_e32 v12, v2
	v_mov_b32_e32 v13, v2
	v_mov_b32_e32 v14, v2
	v_mov_b32_e32 v15, v2
	v_mov_b32_e32 v16, v2
	v_mov_b32_e32 v17, v2
	v_mov_b32_e32 v18, v2
	v_mov_b32_e32 v19, v2
	v_mov_b32_e32 v20, v2
	v_mov_b32_e32 v21, v2
	v_mov_b32_e32 v22, v2
	v_mov_b32_e32 v23, v2
	v_mov_b32_e32 v24, v2
	v_mov_b32_e32 v25, v2
	v_mov_b32_e32 v26, v2
	v_mov_b32_e32 v27, v2
	v_mov_b32_e32 v28, v2
	v_mov_b32_e32 v29, v2
	v_mov_b32_e32 v30, v2
	v_mov_b32_e32 v31, v2
	v_mov_b32_e32 v32, v2
	v_mov_b32_e32 v33, v2
	v_mov_b32_e32 v34, v2
	v_mov_b32_e32 v35, v2
	v_mov_b32_e32 v36, v2
	v_mov_b32_e32 v37, v2
	v_mov_b32_e32 v38, v2
	v_mov_b32_e32 v39, v2
	v_mov_b32_e32 v40, v2
	v_mov_b32_e32 v41, v2
	v_mov_b32_e32 v42, v2
	v_mov_b32_e32 v43, v2
	v_mov_b32_e32 v44, v2
	v_mov_b32_e32 v45, v2
	v_mov_b32_e32 v46, v2
	v_mov_b32_e32 v47, v2
	v_mov_b32_e32 v48, v2
	v_mov_b32_e32 v49, v2
	v_mov_b32_e32 v50, v2
	v_mov_b32_e32 v51, v2
	v_mov_b32_e32 v52, v2
	v_mov_b32_e32 v53, v2
	v_mov_b32_e32 v54, v2
	v_mov_b32_e32 v55, v2
	v_mov_b32_e32 v56, v2
	v_mov_b32_e32 v57, v2
	v_mov_b32_e32 v58, v2
	v_mov_b32_e32 v59, v2
	v_mov_b32_e32 v60, v2
	v_mov_b32_e32 v61, v2
	v_mov_b32_e32 v62, v2
	v_mov_b32_e32 v63, v2
	v_mov_b32_e32 v64, v2
	v_mov_b32_e32 v65, v2
	v_and_b32_e32 v214, 63, v188
	v_lshrrev_b32_e32 v215, 3, v214
	v_and_b32_e32 v216, 7, v214
	v_xor_b32_e32 v216, v216, v215
	v_mul_u32_u24_e32 v246, 0x800, v215
	v_lshl_add_u32 v246, v216, 4, v246
	v_add_u32_e32 v247, 0x4000, v246
	v_add_u32_e32 v248, 0x8000, v246
	v_add_u32_e32 v249, 0xc000, v246
	v_lshrrev_b32_e32 v250, 6, v188
	v_lshlrev_b32_e32 v250, 12, v250
	v_readfirstlane_b32 s98, v66
	v_readfirstlane_b32 s99, v67
	v_readfirstlane_b32 s100, v74
	v_readfirstlane_b32 s101, v75
	s_add_u32 s98, s98, s44
	s_addc_u32 s99, s99, s45
	s_add_u32 s100, s100, s44
	s_addc_u32 s101, s101, s45
	s_waitcnt vmcnt(16) lgkmcnt(0)
	s_barrier

.LBB0_943:
	s_or_b64 exec, exec, s[34:35]
	v_mov_b32_e32 v0, v188
	s_waitcnt lgkmcnt(0)
	s_barrier
	v_readlane_b32 s0, v253, 49
	v_ashrrev_i32_e32 v2, 6, v0
	s_nop 0
	v_add_u32_e32 v18, s0, v2
	v_cmp_gt_i32_e32 vcc, s22, v18
	s_and_saveexec_b64 s[34:35], vcc
	s_movk_i32 s26, 0x6000
	s_mov_b64 s[56:57], 0x4000
	s_cbranch_execz .LBB0_946
	v_readlane_b32 s40, v252, 18
	v_cmp_lt_i32_e32 vcc, v193, v192
	v_readlane_b32 s0, v253, 19
	v_readlane_b32 s48, v252, 26
	v_readlane_b32 s49, v252, 27
	v_readlane_b32 s50, v252, 28
	v_readlane_b32 s51, v252, 29
	v_readlane_b32 s52, v252, 30
	v_readlane_b32 s53, v252, 31
	v_cndmask_b32_e32 v4, v191, v193, vcc
	v_cmp_lt_i32_e32 vcc, v194, v192
	s_lshl_b32 s60, s0, 10
	v_readlane_b32 s54, v252, 32
	v_readlane_b32 s55, v252, 33
	s_mov_b64 s[48:49], s[52:53]
	v_lshlrev_b32_e32 v38, 2, v4
	v_cndmask_b32_e32 v4, v191, v194, vcc
	v_cmp_lt_i32_e32 vcc, v195, v192
	s_lshl_b64 s[0:1], s[60:61], 2
	s_mov_b64 s[50:51], s[54:55]
	v_lshlrev_b32_e32 v39, 2, v4
	v_cndmask_b32_e32 v4, v191, v195, vcc
	v_cmp_lt_i32_e32 vcc, v196, v192
	s_add_u32 s0, s50, s0
	v_and_b32_e32 v3, 63, v0
	v_lshlrev_b32_e32 v40, 2, v4
	v_cndmask_b32_e32 v4, v191, v196, vcc
	v_cmp_lt_i32_e32 vcc, v197, v192
	s_addc_u32 s1, s51, s1
	v_lshlrev_b32_e32 v0, 4, v3
	v_lshlrev_b32_e32 v41, 2, v4
	v_cndmask_b32_e32 v4, v191, v197, vcc
	v_cmp_lt_i32_e32 vcc, v198, v192
	v_lshlrev_b32_e32 v2, 2, v3
	v_lshl_add_u64 v[20:21], s[0:1], 0, v[0:1]
	v_lshlrev_b32_e32 v42, 2, v4
	v_cndmask_b32_e32 v4, v191, v198, vcc
	v_readlane_b32 s0, v253, 40
	v_readlane_b32 s41, v252, 19
	v_readlane_b32 s48, v252, 14
	v_readlane_b32 s50, v251, 2
	v_readlane_b32 s2, v253, 47
	v_lshlrev_b32_e32 v43, 2, v4
	v_or_b32_e32 v4, 0x100, v2
	v_or_b32_e32 v6, 0x200, v2
	v_or_b32_e32 v8, 0x300, v2
	v_lshl_add_u64 v[22:23], s[94:95], 0, v[0:1]
	v_lshlrev_b32_e32 v0, 3, v3
	v_readlane_b32 s1, v253, 41
	s_mov_b32 s27, s25
	v_readlane_b32 s58, v253, 19
	s_mov_b32 s19, 0x800000
	v_readlane_b32 s49, v252, 15
	v_readlane_b32 s51, v251, 3
	v_readlane_b32 s3, v253, 48
	v_lshl_add_u64 v[24:25], s[0:1], 0, v[0:1]
	s_mov_b64 s[40:41], 0
	v_lshlrev_b32_e32 v0, 2, v2
	v_lshlrev_b32_e32 v26, 2, v4
	v_lshlrev_b32_e32 v28, 2, v6
	v_lshlrev_b32_e32 v30, 2, v8
	v_readlane_b32 s42, v252, 20
	v_readlane_b32 s43, v252, 21
	v_readlane_b32 s44, v252, 22
	v_readlane_b32 s45, v252, 23
	v_readlane_b32 s46, v252, 24
	v_readlane_b32 s47, v252, 25
	v_and_b32_e32 v96, 63, v188
	v_lshlrev_b32_e32 v2, 4, v96
	v_lshlrev_b32_e32 v3, 3, v96
	v_lshlrev_b32_e32 v100, 2, v96
	v_xor_b32_e32 v4, 0x80, v100
	v_xor_b32_e32 v5, 0x40, v100
	v_xor_b32_e32 v6, 0x20, v100
	v_xor_b32_e32 v7, 0x10, v100
	v_xor_b32_e32 v8, 0x8, v100
	v_xor_b32_e32 v9, 0x4, v100
	v_readfirstlane_b32 s98, v18
	v_mov_b32_e32 v110, v24
	v_mov_b32_e32 v111, v25
	s_mov_b32 s99, s22
	s_mul_i32 s0, s27, 0x6000
	s_add_u32 s0, s0, 0x3000
	s_add_u32 s100, s2, s0
	s_addc_u32 s101, s3, 0
	v_readfirstlane_b32 s0, v20
	v_readfirstlane_b32 s1, v21
	s_nop 4
	global_load_dwordx4 v[48:51], v2, s[0:1]
	global_load_dwordx4 v[52:55], v2, s[0:1] offset:1024
	global_load_dwordx4 v[56:59], v2, s[0:1] offset:2048
	global_load_dwordx4 v[60:63], v2, s[0:1] offset:3072
	s_lshl_b32 s2, s98, 12
	s_add_u32 s2, s94, s2
	s_addc_u32 s3, s95, 0
	global_load_dwordx4 v[32:35], v2, s[2:3]
	global_load_dwordx4 v[36:39], v2, s[2:3] offset:1024
	global_load_dwordx4 v[40:43], v2, s[2:3] offset:2048
	global_load_dwordx4 v[44:47], v2, s[2:3] offset:3072
	s_waitcnt vmcnt(0)
	s_branch .Lnbody_1
